# EpiRes epilogues (P7/P10): later row groups' base rows pre-touched into L2 while the first group is in flight
# baseline (speedup 1.0000x reference)
.LBB0_1079:
	s_ashr_i32 s17, s16, 31
	s_lshl_b64 s[16:17], s[16:17], 19
	s_lshl_b64 s[22:23], s[28:29], 2
	v_mov_b32_e32 v146, v1
	v_lshl_or_b32 v122, s18, 8, v190
	s_add_u32 s22, s77, s22
	s_addc_u32 s23, s78, s23
	v_add_u32_e32 v150, v122, v146
	v_ashrrev_i32_e32 v151, 31, v150
	v_lshl_add_u64 v[126:127], v[150:151], 2, s[22:23]
	global_load_dwordx4 v[130:133], v[126:127], off offset:16
	global_load_dwordx4 v[134:137], v[126:127], off
	global_load_dwordx4 v[122:125], v[126:127], off offset:528
	s_nop 0
	global_load_dwordx4 v[126:129], v[126:127], off offset:512
	v_readlane_b32 s26, v255, 7
	s_add_u32 s22, s88, s16
	v_readlane_b32 s27, v255, 8
	s_addc_u32 s23, s89, s17
	v_add_u32_e32 v146, v146, v188
	s_andn2_b64 vcc, exec, s[26:27]
	v_readlane_b32 s26, v255, 0
	v_readlane_b32 s30, v255, 2
	s_mov_b64 s[16:17], -1
	v_ashrrev_i32_e32 v147, 31, v146
	v_lshl_add_u64 v[148:149], v[150:151], 1, s[22:23]
	v_readlane_b32 s27, v255, 1
	v_readlane_b32 s31, v255, 3
	s_cbranch_vccnz .LBB0_1081
	v_lshl_add_u64 v[150:151], v[150:151], 2, s[20:21]
	v_lshlrev_b64 v[152:153], 12, v[146:147]
	v_lshl_add_u64 v[164:165], v[150:151], 0, v[152:153]
	global_load_dwordx4 v[152:155], v[164:165], off offset:16
	global_load_dwordx4 v[156:159], v[164:165], off
	global_load_dwordx4 v[160:163], v[164:165], off offset:528
	global_load_dwordx4 v[176:179], v[164:165], off offset:512
	v_add_u32_e32 v164, 16, v146
	v_ashrrev_i32_e32 v165, 31, v164
	v_lshlrev_b64 v[180:181], 12, v[164:165]
	v_lshl_add_u64 v[196:197], v[150:151], 0, v[180:181]
	global_load_dwordx4 v[180:183], v[196:197], off offset:16
	global_load_dwordx4 v[184:187], v[196:197], off
	global_load_dwordx4 v[192:195], v[196:197], off offset:528
	s_nop 0
	global_load_dwordx4 v[196:199], v[196:197], off offset:512
	v_lshlrev_b64 v[250:251], 12, v[146:147]
	v_lshl_add_u64 v[250:251], v[150:151], 0, v[250:251]
	v_add_co_u32_e32 v244, vcc, 0x20000, v250
	s_nop 1
	v_addc_co_u32_e32 v245, vcc, 0, v251, vcc
	global_load_dwordx4 v[236:239], v[244:245], off
	global_load_dwordx4 v[240:243], v[244:245], off offset:512
	v_add_co_u32_e32 v246, vcc, 0x30000, v250
	s_nop 1
	v_addc_co_u32_e32 v247, vcc, 0, v251, vcc
	global_load_dwordx4 v[236:239], v[246:247], off
	global_load_dwordx4 v[240:243], v[246:247], off offset:512
	v_add_co_u32_e32 v248, vcc, 0x80000, v250
	s_nop 1
	v_addc_co_u32_e32 v249, vcc, 0, v251, vcc
	global_load_dwordx4 v[236:239], v[248:249], off
	global_load_dwordx4 v[240:243], v[248:249], off offset:512
	v_add_co_u32_e32 v244, vcc, 0x90000, v250
	s_nop 1
	v_addc_co_u32_e32 v245, vcc, 0, v251, vcc
	global_load_dwordx4 v[236:239], v[244:245], off
	global_load_dwordx4 v[240:243], v[244:245], off offset:512
	v_add_co_u32_e32 v246, vcc, 0xa0000, v250
	s_nop 1
	v_addc_co_u32_e32 v247, vcc, 0, v251, vcc
	global_load_dwordx4 v[236:239], v[246:247], off
	global_load_dwordx4 v[240:243], v[246:247], off offset:512
	v_add_co_u32_e32 v248, vcc, 0xb0000, v250
	s_nop 1
	v_addc_co_u32_e32 v249, vcc, 0, v251, vcc
	global_load_dwordx4 v[236:239], v[248:249], off
	global_load_dwordx4 v[240:243], v[248:249], off offset:512
	v_lshlrev_b64 v[200:201], 11, v[146:147]
	v_lshl_add_u64 v[200:201], v[148:149], 0, v[200:201]
	s_mov_b64 s[16:17], 0
	s_waitcnt vmcnt(12)
	v_pk_fma_f32 v[202:203], v[140:141], v[132:133], v[154:155]
	v_pk_fma_f32 v[158:159], v[144:145], v[136:137], v[158:159]
	v_pk_fma_f32 v[156:157], v[142:143], v[134:135], v[156:157]
	v_pk_fma_f32 v[154:155], v[138:139], v[130:131], v[152:153]
	v_cvt_pk_bf16_f32 v152, v156, v157
	v_cvt_pk_bf16_f32 v153, v158, v159
	v_pk_fma_f32 v[156:157], v[116:117], v[124:125], v[162:163]
	v_cvt_pk_bf16_f32 v154, v154, v155
	v_cvt_pk_bf16_f32 v155, v202, v203
	global_store_dwordx4 v[200:201], v[152:155], off
	v_pk_fma_f32 v[158:159], v[114:115], v[122:123], v[160:161]
	v_pk_fma_f32 v[160:161], v[106:107], v[130:131], v[180:181]
	v_pk_fma_f32 v[152:153], v[118:119], v[126:127], v[176:177]
	v_pk_fma_f32 v[154:155], v[120:121], v[128:129], v[178:179]
	v_cvt_pk_bf16_f32 v152, v152, v153
	s_nop 0
	v_cvt_pk_bf16_f32 v153, v154, v155
	v_cvt_pk_bf16_f32 v154, v158, v159
	v_cvt_pk_bf16_f32 v155, v156, v157
	global_store_dwordx4 v[200:201], v[152:155], off offset:256
	v_pk_fma_f32 v[158:159], v[108:109], v[132:133], v[182:183]
	v_add_u32_e32 v200, 48, v146
	v_lshlrev_b64 v[152:153], 11, v[164:165]
	v_lshl_add_u64 v[156:157], v[148:149], 0, v[152:153]
	v_pk_fma_f32 v[152:153], v[110:111], v[134:135], v[184:185]
	v_pk_fma_f32 v[154:155], v[112:113], v[136:137], v[186:187]
	v_cvt_pk_bf16_f32 v152, v152, v153
	v_add_u32_e32 v164, 32, v146
	v_cvt_pk_bf16_f32 v153, v154, v155
	v_cvt_pk_bf16_f32 v154, v160, v161
	v_cvt_pk_bf16_f32 v155, v158, v159
	global_store_dwordx4 v[156:157], v[152:155], off
	v_ashrrev_i32_e32 v165, 31, v164
	v_pk_fma_f32 v[158:159], v[100:101], v[124:125], v[194:195]
	v_pk_fma_f32 v[152:153], v[102:103], v[126:127], v[196:197]
	v_pk_fma_f32 v[154:155], v[104:105], v[128:129], v[198:199]
	v_cvt_pk_bf16_f32 v152, v152, v153
	v_pk_fma_f32 v[160:161], v[98:99], v[122:123], v[192:193]
	v_cvt_pk_bf16_f32 v153, v154, v155
	v_ashrrev_i32_e32 v201, 31, v200
	v_cvt_pk_bf16_f32 v154, v160, v161
	v_cvt_pk_bf16_f32 v155, v158, v159
	global_store_dwordx4 v[156:157], v[152:155], off offset:256
	v_lshlrev_b64 v[180:181], 12, v[200:201]
	v_lshl_add_u64 v[196:197], v[150:151], 0, v[180:181]
	v_lshlrev_b64 v[152:153], 12, v[164:165]
	v_lshl_add_u64 v[176:177], v[150:151], 0, v[152:153]
	global_load_dwordx4 v[152:155], v[176:177], off offset:16
	global_load_dwordx4 v[156:159], v[176:177], off
	global_load_dwordx4 v[160:163], v[176:177], off offset:528
	s_nop 0
	global_load_dwordx4 v[176:179], v[176:177], off offset:512
	s_nop 0
	global_load_dwordx4 v[180:183], v[196:197], off offset:16
	global_load_dwordx4 v[184:187], v[196:197], off
	global_load_dwordx4 v[192:195], v[196:197], off offset:528
	s_nop 0
	global_load_dwordx4 v[196:199], v[196:197], off offset:512
	v_lshlrev_b64 v[164:165], 11, v[164:165]
	v_lshl_add_u64 v[164:165], v[148:149], 0, v[164:165]
	s_waitcnt vmcnt(0)
	v_pk_fma_f32 v[202:203], v[92:93], v[132:133], v[154:155]
	v_pk_fma_f32 v[158:159], v[96:97], v[136:137], v[158:159]
	v_pk_fma_f32 v[156:157], v[94:95], v[134:135], v[156:157]
	v_pk_fma_f32 v[154:155], v[90:91], v[130:131], v[152:153]
	v_cvt_pk_bf16_f32 v152, v156, v157
	v_cvt_pk_bf16_f32 v153, v158, v159
	v_pk_fma_f32 v[156:157], v[84:85], v[124:125], v[162:163]
	v_cvt_pk_bf16_f32 v154, v154, v155
	v_cvt_pk_bf16_f32 v155, v202, v203
	global_store_dwordx4 v[164:165], v[152:155], off
	v_pk_fma_f32 v[158:159], v[82:83], v[122:123], v[160:161]
	v_pk_fma_f32 v[160:161], v[74:75], v[130:131], v[180:181]
	v_pk_fma_f32 v[152:153], v[86:87], v[126:127], v[176:177]
	v_pk_fma_f32 v[154:155], v[88:89], v[128:129], v[178:179]
	v_cvt_pk_bf16_f32 v152, v152, v153
	s_nop 0
	v_cvt_pk_bf16_f32 v153, v154, v155
	v_cvt_pk_bf16_f32 v154, v158, v159
	v_cvt_pk_bf16_f32 v155, v156, v157
	global_store_dwordx4 v[164:165], v[152:155], off offset:256
	v_pk_fma_f32 v[158:159], v[76:77], v[132:133], v[182:183]
	v_add_u32_e32 v164, 0x80, v146
	v_lshlrev_b64 v[152:153], 11, v[200:201]
	v_lshl_add_u64 v[156:157], v[148:149], 0, v[152:153]
	v_pk_fma_f32 v[152:153], v[78:79], v[134:135], v[184:185]
	v_pk_fma_f32 v[154:155], v[80:81], v[136:137], v[186:187]
	v_cvt_pk_bf16_f32 v152, v152, v153
	v_ashrrev_i32_e32 v165, 31, v164
	v_cvt_pk_bf16_f32 v153, v154, v155
	v_cvt_pk_bf16_f32 v154, v160, v161
	v_cvt_pk_bf16_f32 v155, v158, v159
	global_store_dwordx4 v[156:157], v[152:155], off
	v_pk_fma_f32 v[158:159], v[68:69], v[124:125], v[194:195]
	v_pk_fma_f32 v[160:161], v[66:67], v[122:123], v[192:193]
	v_pk_fma_f32 v[152:153], v[70:71], v[126:127], v[196:197]
	v_pk_fma_f32 v[154:155], v[72:73], v[128:129], v[198:199]
	v_cvt_pk_bf16_f32 v152, v152, v153
	v_add_u32_e32 v200, 0x90, v146
	v_cvt_pk_bf16_f32 v153, v154, v155
	v_cvt_pk_bf16_f32 v154, v160, v161
	v_cvt_pk_bf16_f32 v155, v158, v159
	global_store_dwordx4 v[156:157], v[152:155], off offset:256
	v_ashrrev_i32_e32 v201, 31, v200
	v_lshlrev_b64 v[180:181], 12, v[200:201]
	v_lshlrev_b64 v[152:153], 12, v[164:165]
	v_lshl_add_u64 v[176:177], v[150:151], 0, v[152:153]
	global_load_dwordx4 v[152:155], v[176:177], off offset:16
	global_load_dwordx4 v[156:159], v[176:177], off
	global_load_dwordx4 v[160:163], v[176:177], off offset:528
	s_nop 0
	global_load_dwordx4 v[176:179], v[176:177], off offset:512
	v_lshl_add_u64 v[196:197], v[150:151], 0, v[180:181]
	global_load_dwordx4 v[180:183], v[196:197], off offset:16
	global_load_dwordx4 v[184:187], v[196:197], off
	global_load_dwordx4 v[192:195], v[196:197], off offset:528
	s_nop 0
	global_load_dwordx4 v[196:199], v[196:197], off offset:512
	v_lshlrev_b64 v[164:165], 11, v[164:165]
	v_lshl_add_u64 v[164:165], v[148:149], 0, v[164:165]
	s_waitcnt vmcnt(0)
	v_pk_fma_f32 v[202:203], v[60:61], v[132:133], v[154:155]
	v_pk_fma_f32 v[158:159], v[64:65], v[136:137], v[158:159]
	v_pk_fma_f32 v[156:157], v[62:63], v[134:135], v[156:157]
	v_pk_fma_f32 v[154:155], v[58:59], v[130:131], v[152:153]
	v_cvt_pk_bf16_f32 v152, v156, v157
	v_cvt_pk_bf16_f32 v153, v158, v159
	v_pk_fma_f32 v[156:157], v[52:53], v[124:125], v[162:163]
	v_cvt_pk_bf16_f32 v154, v154, v155
	v_cvt_pk_bf16_f32 v155, v202, v203
	global_store_dwordx4 v[164:165], v[152:155], off
	v_pk_fma_f32 v[158:159], v[50:51], v[122:123], v[160:161]
	v_pk_fma_f32 v[160:161], v[42:43], v[130:131], v[180:181]
	v_pk_fma_f32 v[152:153], v[54:55], v[126:127], v[176:177]
	v_pk_fma_f32 v[154:155], v[56:57], v[128:129], v[178:179]
	v_cvt_pk_bf16_f32 v152, v152, v153
	s_nop 0
	v_cvt_pk_bf16_f32 v153, v154, v155
	v_cvt_pk_bf16_f32 v154, v158, v159
	v_cvt_pk_bf16_f32 v155, v156, v157
	global_store_dwordx4 v[164:165], v[152:155], off offset:256
	v_pk_fma_f32 v[158:159], v[44:45], v[132:133], v[182:183]
	v_add_u32_e32 v164, 0xa0, v146
	v_lshlrev_b64 v[152:153], 11, v[200:201]
	v_lshl_add_u64 v[156:157], v[148:149], 0, v[152:153]
	v_pk_fma_f32 v[152:153], v[46:47], v[134:135], v[184:185]
	v_pk_fma_f32 v[154:155], v[48:49], v[136:137], v[186:187]
	v_cvt_pk_bf16_f32 v152, v152, v153
	v_ashrrev_i32_e32 v165, 31, v164
	v_cvt_pk_bf16_f32 v153, v154, v155
	v_cvt_pk_bf16_f32 v154, v160, v161
	v_cvt_pk_bf16_f32 v155, v158, v159
	global_store_dwordx4 v[156:157], v[152:155], off
	v_pk_fma_f32 v[158:159], v[36:37], v[124:125], v[194:195]
	v_pk_fma_f32 v[160:161], v[34:35], v[122:123], v[192:193]
	v_pk_fma_f32 v[152:153], v[38:39], v[126:127], v[196:197]
	v_pk_fma_f32 v[154:155], v[40:41], v[128:129], v[198:199]
	v_cvt_pk_bf16_f32 v152, v152, v153
	v_add_u32_e32 v200, 0xb0, v146
	v_cvt_pk_bf16_f32 v153, v154, v155
	v_cvt_pk_bf16_f32 v154, v160, v161
	v_cvt_pk_bf16_f32 v155, v158, v159
	global_store_dwordx4 v[156:157], v[152:155], off offset:256
	v_ashrrev_i32_e32 v201, 31, v200
	v_lshlrev_b64 v[180:181], 12, v[200:201]
	v_lshlrev_b64 v[152:153], 12, v[164:165]
	v_lshl_add_u64 v[176:177], v[150:151], 0, v[152:153]
	global_load_dwordx4 v[152:155], v[176:177], off offset:16
	global_load_dwordx4 v[156:159], v[176:177], off
	global_load_dwordx4 v[160:163], v[176:177], off offset:528
	s_nop 0
	global_load_dwordx4 v[176:179], v[176:177], off offset:512
	v_lshl_add_u64 v[150:151], v[150:151], 0, v[180:181]
	global_load_dwordx4 v[180:183], v[150:151], off offset:16
	global_load_dwordx4 v[184:187], v[150:151], off
	global_load_dwordx4 v[192:195], v[150:151], off offset:528
	global_load_dwordx4 v[196:199], v[150:151], off offset:512
	v_lshlrev_b64 v[150:151], 11, v[164:165]
	v_lshl_add_u64 v[164:165], v[148:149], 0, v[150:151]
	s_waitcnt vmcnt(0)
	v_pk_fma_f32 v[152:153], v[26:27], v[130:131], v[152:153]
	v_pk_fma_f32 v[150:151], v[30:31], v[134:135], v[156:157]
	v_pk_fma_f32 v[158:159], v[32:33], v[136:137], v[158:159]
	v_cvt_pk_bf16_f32 v150, v150, v151
	v_pk_fma_f32 v[154:155], v[28:29], v[132:133], v[154:155]
	v_cvt_pk_bf16_f32 v151, v158, v159
	v_cvt_pk_bf16_f32 v152, v152, v153
	v_pk_fma_f32 v[156:157], v[18:19], v[122:123], v[160:161]
	v_cvt_pk_bf16_f32 v153, v154, v155
	global_store_dwordx4 v[164:165], v[150:153], off
	v_pk_fma_f32 v[154:155], v[20:21], v[124:125], v[162:163]
	v_pk_fma_f32 v[158:159], v[10:11], v[130:131], v[180:181]
	v_pk_fma_f32 v[150:151], v[22:23], v[126:127], v[176:177]
	v_pk_fma_f32 v[152:153], v[24:25], v[128:129], v[178:179]
	v_cvt_pk_bf16_f32 v150, v150, v151
	s_nop 0
	v_cvt_pk_bf16_f32 v151, v152, v153
	v_cvt_pk_bf16_f32 v152, v156, v157
	v_cvt_pk_bf16_f32 v153, v154, v155
	global_store_dwordx4 v[164:165], v[150:153], off offset:256
	v_pk_fma_f32 v[156:157], v[12:13], v[132:133], v[182:183]
	s_nop 0
	v_lshlrev_b64 v[150:151], 11, v[200:201]
	v_lshl_add_u64 v[154:155], v[148:149], 0, v[150:151]
	v_pk_fma_f32 v[152:153], v[16:17], v[136:137], v[186:187]
	v_pk_fma_f32 v[150:151], v[14:15], v[134:135], v[184:185]
	s_nop 0
	v_cvt_pk_bf16_f32 v150, v150, v151
	v_cvt_pk_bf16_f32 v151, v152, v153
	v_cvt_pk_bf16_f32 v152, v158, v159
	v_cvt_pk_bf16_f32 v153, v156, v157
	global_store_dwordx4 v[154:155], v[150:153], off
	v_pk_fma_f32 v[156:157], v[4:5], v[124:125], v[194:195]
	v_pk_fma_f32 v[158:159], v[2:3], v[122:123], v[192:193]
	v_pk_fma_f32 v[152:153], v[8:9], v[128:129], v[198:199]
	v_pk_fma_f32 v[150:151], v[6:7], v[126:127], v[196:197]
	s_nop 0
	v_cvt_pk_bf16_f32 v150, v150, v151
	v_cvt_pk_bf16_f32 v151, v152, v153
	v_cvt_pk_bf16_f32 v152, v158, v159
	v_cvt_pk_bf16_f32 v153, v156, v157
	global_store_dwordx4 v[154:155], v[150:153], off offset:256
.LBB0_1081:
	s_andn2_b64 vcc, exec, s[16:17]
	s_cbranch_vccnz .LBB0_1070
	v_lshlrev_b64 v[146:147], 11, v[146:147]
	v_lshl_add_u64 v[176:177], v[148:149], 0, v[146:147]
	global_load_dwordx4 v[192:195], v[176:177], off
	global_load_dwordx4 v[196:199], v[176:177], off offset:256
	v_add_co_u32_e32 v204, vcc, 0x8000, v176
	s_mov_b64 s[16:17], 0x8000
	s_nop 0
	v_addc_co_u32_e32 v205, vcc, 0, v177, vcc
	v_lshl_add_u64 v[186:187], v[176:177], 0, s[16:17]
	global_load_dwordx4 v[200:203], v[204:205], off
	global_load_dwordx4 v[162:165], v[186:187], off offset:256
	s_mov_b32 s7, 0x10000
	v_add_co_u32_e32 v184, vcc, s7, v176
	s_mov_b64 s[16:17], 0x10000
	s_nop 0
	v_addc_co_u32_e32 v185, vcc, 0, v177, vcc
	v_lshl_add_u64 v[182:183], v[176:177], 0, s[16:17]
	global_load_dwordx4 v[158:161], v[184:185], off
	global_load_dwordx4 v[154:157], v[182:183], off offset:256
	s_mov_b32 s7, 0x18000
	v_add_co_u32_e32 v180, vcc, s7, v176
	s_mov_b64 s[16:17], 0x18000
	s_nop 0
	v_addc_co_u32_e32 v181, vcc, 0, v177, vcc
	v_lshl_add_u64 v[178:179], v[176:177], 0, s[16:17]
	global_load_dwordx4 v[150:153], v[180:181], off
	global_load_dwordx4 v[146:149], v[178:179], off offset:256
	v_add_co_u32_e32 v244, vcc, 0x40000, v176
	s_nop 1
	v_addc_co_u32_e32 v245, vcc, 0, v177, vcc
	global_load_dwordx4 v[236:239], v[244:245], off
	global_load_dwordx4 v[240:243], v[244:245], off offset:256
	v_add_co_u32_e32 v246, vcc, 0x48000, v176
	s_nop 1
	v_addc_co_u32_e32 v247, vcc, 0, v177, vcc
	global_load_dwordx4 v[236:239], v[246:247], off
	global_load_dwordx4 v[240:243], v[246:247], off offset:256
	v_add_co_u32_e32 v248, vcc, 0x50000, v176
	s_nop 1
	v_addc_co_u32_e32 v249, vcc, 0, v177, vcc
	global_load_dwordx4 v[236:239], v[248:249], off
	global_load_dwordx4 v[240:243], v[248:249], off offset:256
	v_add_co_u32_e32 v244, vcc, 0x58000, v176
	s_nop 1
	v_addc_co_u32_e32 v245, vcc, 0, v177, vcc
	global_load_dwordx4 v[236:239], v[244:245], off
	global_load_dwordx4 v[240:243], v[244:245], off offset:256
	s_mov_b32 s7, 0x40000
	s_mov_b64 s[16:17], 0x48000
	s_waitcnt vmcnt(8)
	v_lshlrev_b32_e32 v206, 16, v192
	v_and_b32_e32 v207, 0xffff0000, v192
	v_lshlrev_b32_e32 v192, 16, v193
	v_and_b32_e32 v193, 0xffff0000, v193
	v_lshlrev_b32_e32 v208, 16, v194
	v_and_b32_e32 v209, 0xffff0000, v194
	v_lshlrev_b32_e32 v194, 16, v195
	v_and_b32_e32 v195, 0xffff0000, v195
	v_pk_fma_f32 v[144:145], v[144:145], v[136:137], v[192:193]
	v_pk_fma_f32 v[142:143], v[142:143], v[134:135], v[206:207]
	v_pk_fma_f32 v[192:193], v[140:141], v[132:133], v[194:195]
	v_pk_fma_f32 v[140:141], v[138:139], v[130:131], v[208:209]
	v_cvt_pk_bf16_f32 v138, v142, v143
	v_cvt_pk_bf16_f32 v139, v144, v145
	v_lshlrev_b32_e32 v142, 16, v198
	v_cvt_pk_bf16_f32 v140, v140, v141
	v_cvt_pk_bf16_f32 v141, v192, v193
	global_store_dwordx4 v[176:177], v[138:141], off
	v_and_b32_e32 v143, 0xffff0000, v198
	v_lshlrev_b32_e32 v144, 16, v199
	v_lshlrev_b32_e32 v138, 16, v196
	v_and_b32_e32 v139, 0xffff0000, v196
	v_and_b32_e32 v145, 0xffff0000, v199
	v_lshlrev_b32_e32 v140, 16, v197
	v_and_b32_e32 v141, 0xffff0000, v197
	v_pk_fma_f32 v[118:119], v[118:119], v[126:127], v[138:139]
	v_pk_fma_f32 v[138:139], v[116:117], v[124:125], v[144:145]
	v_pk_fma_f32 v[116:117], v[114:115], v[122:123], v[142:143]
	v_pk_fma_f32 v[120:121], v[120:121], v[128:129], v[140:141]
	v_cvt_pk_bf16_f32 v114, v118, v119
	v_lshlrev_b32_e32 v118, 16, v202
	v_cvt_pk_bf16_f32 v115, v120, v121
	v_cvt_pk_bf16_f32 v116, v116, v117
	v_cvt_pk_bf16_f32 v117, v138, v139
	global_store_dwordx4 v[176:177], v[114:117], off offset:256
	v_and_b32_e32 v119, 0xffff0000, v202
	v_lshlrev_b32_e32 v120, 16, v203
	v_lshlrev_b32_e32 v114, 16, v200
	v_and_b32_e32 v115, 0xffff0000, v200
	v_lshlrev_b32_e32 v116, 16, v201
	v_and_b32_e32 v117, 0xffff0000, v201
	v_and_b32_e32 v121, 0xffff0000, v203
	v_pk_fma_f32 v[112:113], v[112:113], v[136:137], v[116:117]
	v_pk_fma_f32 v[110:111], v[110:111], v[134:135], v[114:115]
	v_pk_fma_f32 v[114:115], v[108:109], v[132:133], v[120:121]
	v_pk_fma_f32 v[108:109], v[106:107], v[130:131], v[118:119]
	v_cvt_pk_bf16_f32 v106, v110, v111
	v_cvt_pk_bf16_f32 v107, v112, v113
	v_lshlrev_b32_e32 v110, 16, v164
	v_cvt_pk_bf16_f32 v108, v108, v109
	v_cvt_pk_bf16_f32 v109, v114, v115
	global_store_dwordx4 v[204:205], v[106:109], off
	v_and_b32_e32 v111, 0xffff0000, v164
	v_lshlrev_b32_e32 v112, 16, v165
	v_lshlrev_b32_e32 v106, 16, v162
	v_and_b32_e32 v107, 0xffff0000, v162
	v_and_b32_e32 v113, 0xffff0000, v165
	v_lshlrev_b32_e32 v108, 16, v163
	v_and_b32_e32 v109, 0xffff0000, v163
	v_pk_fma_f32 v[102:103], v[102:103], v[126:127], v[106:107]
	v_pk_fma_f32 v[106:107], v[100:101], v[124:125], v[112:113]
	v_pk_fma_f32 v[100:101], v[98:99], v[122:123], v[110:111]
	v_pk_fma_f32 v[104:105], v[104:105], v[128:129], v[108:109]
	v_cvt_pk_bf16_f32 v98, v102, v103
	v_lshlrev_b32_e32 v102, 16, v160
	v_cvt_pk_bf16_f32 v99, v104, v105
	v_cvt_pk_bf16_f32 v100, v100, v101
	v_cvt_pk_bf16_f32 v101, v106, v107
	global_store_dwordx4 v[186:187], v[98:101], off offset:256
	v_and_b32_e32 v103, 0xffff0000, v160
	v_lshlrev_b32_e32 v104, 16, v161
	v_lshlrev_b32_e32 v98, 16, v158
	v_and_b32_e32 v99, 0xffff0000, v158
	v_lshlrev_b32_e32 v100, 16, v159
	v_and_b32_e32 v101, 0xffff0000, v159
	v_and_b32_e32 v105, 0xffff0000, v161
	v_pk_fma_f32 v[96:97], v[96:97], v[136:137], v[100:101]
	v_pk_fma_f32 v[94:95], v[94:95], v[134:135], v[98:99]
	v_pk_fma_f32 v[98:99], v[92:93], v[132:133], v[104:105]
	v_pk_fma_f32 v[92:93], v[90:91], v[130:131], v[102:103]
	v_cvt_pk_bf16_f32 v90, v94, v95
	v_cvt_pk_bf16_f32 v91, v96, v97
	v_lshlrev_b32_e32 v94, 16, v156
	v_cvt_pk_bf16_f32 v92, v92, v93
	v_cvt_pk_bf16_f32 v93, v98, v99
	global_store_dwordx4 v[184:185], v[90:93], off
	v_and_b32_e32 v95, 0xffff0000, v156
	v_lshlrev_b32_e32 v96, 16, v157
	v_lshlrev_b32_e32 v90, 16, v154
	v_and_b32_e32 v91, 0xffff0000, v154
	v_and_b32_e32 v97, 0xffff0000, v157
	v_lshlrev_b32_e32 v92, 16, v155
	v_and_b32_e32 v93, 0xffff0000, v155
	v_pk_fma_f32 v[86:87], v[86:87], v[126:127], v[90:91]
	v_pk_fma_f32 v[90:91], v[84:85], v[124:125], v[96:97]
	v_pk_fma_f32 v[84:85], v[82:83], v[122:123], v[94:95]
	v_pk_fma_f32 v[88:89], v[88:89], v[128:129], v[92:93]
	v_cvt_pk_bf16_f32 v82, v86, v87
	v_lshlrev_b32_e32 v86, 16, v152
	v_cvt_pk_bf16_f32 v83, v88, v89
	v_cvt_pk_bf16_f32 v84, v84, v85
	v_cvt_pk_bf16_f32 v85, v90, v91
	global_store_dwordx4 v[182:183], v[82:85], off offset:256
	v_and_b32_e32 v87, 0xffff0000, v152
	v_lshlrev_b32_e32 v88, 16, v153
	v_lshlrev_b32_e32 v82, 16, v150
	v_and_b32_e32 v83, 0xffff0000, v150
	v_lshlrev_b32_e32 v84, 16, v151
	v_and_b32_e32 v85, 0xffff0000, v151
	v_and_b32_e32 v89, 0xffff0000, v153
	v_pk_fma_f32 v[80:81], v[80:81], v[136:137], v[84:85]
	v_pk_fma_f32 v[78:79], v[78:79], v[134:135], v[82:83]
	v_pk_fma_f32 v[82:83], v[76:77], v[132:133], v[88:89]
	v_pk_fma_f32 v[76:77], v[74:75], v[130:131], v[86:87]
	v_cvt_pk_bf16_f32 v74, v78, v79
	v_cvt_pk_bf16_f32 v75, v80, v81
	v_lshlrev_b32_e32 v78, 16, v148
	v_cvt_pk_bf16_f32 v76, v76, v77
	v_cvt_pk_bf16_f32 v77, v82, v83
	global_store_dwordx4 v[180:181], v[74:77], off
	v_and_b32_e32 v79, 0xffff0000, v148
	v_lshlrev_b32_e32 v80, 16, v149
	v_lshlrev_b32_e32 v74, 16, v146
	v_and_b32_e32 v75, 0xffff0000, v146
	v_and_b32_e32 v81, 0xffff0000, v149
	v_lshlrev_b32_e32 v76, 16, v147
	v_and_b32_e32 v77, 0xffff0000, v147
	v_pk_fma_f32 v[70:71], v[70:71], v[126:127], v[74:75]
	v_pk_fma_f32 v[74:75], v[68:69], v[124:125], v[80:81]
	v_pk_fma_f32 v[68:69], v[66:67], v[122:123], v[78:79]
	v_pk_fma_f32 v[72:73], v[72:73], v[128:129], v[76:77]
	v_cvt_pk_bf16_f32 v66, v70, v71
	v_add_co_u32_e32 v106, vcc, s7, v176
	v_cvt_pk_bf16_f32 v67, v72, v73
	v_cvt_pk_bf16_f32 v68, v68, v69
	v_cvt_pk_bf16_f32 v69, v74, v75
	global_store_dwordx4 v[178:179], v[66:69], off offset:256
	s_nop 0
	v_addc_co_u32_e32 v107, vcc, 0, v177, vcc
	v_lshl_add_u64 v[104:105], v[176:177], 0, s[2:3]
	global_load_dwordx4 v[80:83], v[106:107], off
	global_load_dwordx4 v[84:87], v[104:105], off offset:256
	s_mov_b32 s7, 0x48000
	v_add_co_u32_e32 v110, vcc, s7, v176
	v_lshl_add_u64 v[108:109], v[176:177], 0, s[16:17]
	s_nop 0
	v_addc_co_u32_e32 v111, vcc, 0, v177, vcc
	global_load_dwordx4 v[88:91], v[110:111], off
	global_load_dwordx4 v[92:95], v[108:109], off offset:256
	s_mov_b32 s7, 0x50000
	v_add_co_u32_e32 v112, vcc, s7, v176
	s_mov_b64 s[16:17], 0x50000
	s_nop 0
	v_addc_co_u32_e32 v113, vcc, 0, v177, vcc
	v_lshl_add_u64 v[78:79], v[176:177], 0, s[16:17]
	global_load_dwordx4 v[96:99], v[112:113], off
	global_load_dwordx4 v[100:103], v[78:79], off offset:256
	s_mov_b32 s7, 0x58000
	v_add_co_u32_e32 v76, vcc, s7, v176
	s_mov_b64 s[16:17], 0x58000
	s_nop 0
	v_addc_co_u32_e32 v77, vcc, 0, v177, vcc
	v_lshl_add_u64 v[74:75], v[176:177], 0, s[16:17]
	global_load_dwordx4 v[70:73], v[76:77], off
	global_load_dwordx4 v[66:69], v[74:75], off offset:256
	s_waitcnt vmcnt(0)
	v_lshlrev_b32_e32 v114, 16, v80
	v_and_b32_e32 v115, 0xffff0000, v80
	v_lshlrev_b32_e32 v80, 16, v81
	v_and_b32_e32 v81, 0xffff0000, v81
	v_lshlrev_b32_e32 v116, 16, v82
	v_and_b32_e32 v117, 0xffff0000, v82
	v_lshlrev_b32_e32 v82, 16, v83
	v_and_b32_e32 v83, 0xffff0000, v83
	v_pk_fma_f32 v[64:65], v[64:65], v[136:137], v[80:81]
	v_pk_fma_f32 v[62:63], v[62:63], v[134:135], v[114:115]
	v_pk_fma_f32 v[80:81], v[60:61], v[132:133], v[82:83]
	v_pk_fma_f32 v[60:61], v[58:59], v[130:131], v[116:117]
	v_cvt_pk_bf16_f32 v58, v62, v63
	v_cvt_pk_bf16_f32 v59, v64, v65
	v_lshlrev_b32_e32 v62, 16, v86
	v_cvt_pk_bf16_f32 v60, v60, v61
	v_cvt_pk_bf16_f32 v61, v80, v81
	global_store_dwordx4 v[106:107], v[58:61], off
	v_and_b32_e32 v63, 0xffff0000, v86
	v_lshlrev_b32_e32 v64, 16, v87
	v_lshlrev_b32_e32 v58, 16, v84
	v_and_b32_e32 v59, 0xffff0000, v84
	v_and_b32_e32 v65, 0xffff0000, v87
	v_lshlrev_b32_e32 v60, 16, v85
	v_and_b32_e32 v61, 0xffff0000, v85
	v_pk_fma_f32 v[54:55], v[54:55], v[126:127], v[58:59]
	v_pk_fma_f32 v[58:59], v[52:53], v[124:125], v[64:65]
	v_pk_fma_f32 v[52:53], v[50:51], v[122:123], v[62:63]
	v_pk_fma_f32 v[56:57], v[56:57], v[128:129], v[60:61]
	v_cvt_pk_bf16_f32 v50, v54, v55
	v_lshlrev_b32_e32 v54, 16, v90
	v_cvt_pk_bf16_f32 v51, v56, v57
	v_cvt_pk_bf16_f32 v52, v52, v53
	v_cvt_pk_bf16_f32 v53, v58, v59
	global_store_dwordx4 v[104:105], v[50:53], off offset:256
	v_and_b32_e32 v55, 0xffff0000, v90
	v_lshlrev_b32_e32 v56, 16, v91
	v_lshlrev_b32_e32 v50, 16, v88
	v_and_b32_e32 v51, 0xffff0000, v88
	v_lshlrev_b32_e32 v52, 16, v89
	v_and_b32_e32 v53, 0xffff0000, v89
	v_and_b32_e32 v57, 0xffff0000, v91
	v_pk_fma_f32 v[48:49], v[48:49], v[136:137], v[52:53]
	v_pk_fma_f32 v[46:47], v[46:47], v[134:135], v[50:51]
	v_pk_fma_f32 v[50:51], v[44:45], v[132:133], v[56:57]
	v_pk_fma_f32 v[44:45], v[42:43], v[130:131], v[54:55]
	v_cvt_pk_bf16_f32 v42, v46, v47
	v_cvt_pk_bf16_f32 v43, v48, v49
	v_lshlrev_b32_e32 v46, 16, v94
	v_cvt_pk_bf16_f32 v44, v44, v45
	v_cvt_pk_bf16_f32 v45, v50, v51
	global_store_dwordx4 v[110:111], v[42:45], off
	v_and_b32_e32 v47, 0xffff0000, v94
	v_lshlrev_b32_e32 v48, 16, v95
	v_lshlrev_b32_e32 v42, 16, v92
	v_and_b32_e32 v43, 0xffff0000, v92
	v_and_b32_e32 v49, 0xffff0000, v95
	v_lshlrev_b32_e32 v44, 16, v93
	v_and_b32_e32 v45, 0xffff0000, v93
	v_pk_fma_f32 v[38:39], v[38:39], v[126:127], v[42:43]
	v_pk_fma_f32 v[42:43], v[36:37], v[124:125], v[48:49]
	v_pk_fma_f32 v[36:37], v[34:35], v[122:123], v[46:47]
	v_pk_fma_f32 v[40:41], v[40:41], v[128:129], v[44:45]
	v_cvt_pk_bf16_f32 v34, v38, v39
	v_lshlrev_b32_e32 v38, 16, v98
	v_cvt_pk_bf16_f32 v35, v40, v41
	v_cvt_pk_bf16_f32 v36, v36, v37
	v_cvt_pk_bf16_f32 v37, v42, v43
	global_store_dwordx4 v[108:109], v[34:37], off offset:256
	v_and_b32_e32 v39, 0xffff0000, v98
	v_lshlrev_b32_e32 v40, 16, v99
	v_lshlrev_b32_e32 v34, 16, v96
	v_and_b32_e32 v35, 0xffff0000, v96
	v_lshlrev_b32_e32 v36, 16, v97
	v_and_b32_e32 v37, 0xffff0000, v97
	v_and_b32_e32 v41, 0xffff0000, v99
	v_pk_fma_f32 v[32:33], v[32:33], v[136:137], v[36:37]
	v_pk_fma_f32 v[30:31], v[30:31], v[134:135], v[34:35]
	v_pk_fma_f32 v[34:35], v[28:29], v[132:133], v[40:41]
	v_pk_fma_f32 v[28:29], v[26:27], v[130:131], v[38:39]
	v_cvt_pk_bf16_f32 v26, v30, v31
	v_cvt_pk_bf16_f32 v27, v32, v33
	v_lshlrev_b32_e32 v30, 16, v102
	v_cvt_pk_bf16_f32 v28, v28, v29
	v_cvt_pk_bf16_f32 v29, v34, v35
	global_store_dwordx4 v[112:113], v[26:29], off
	v_and_b32_e32 v31, 0xffff0000, v102
	v_lshlrev_b32_e32 v32, 16, v103
	v_lshlrev_b32_e32 v26, 16, v100
	v_and_b32_e32 v27, 0xffff0000, v100
	v_and_b32_e32 v33, 0xffff0000, v103
	v_lshlrev_b32_e32 v28, 16, v101
	v_and_b32_e32 v29, 0xffff0000, v101
	v_pk_fma_f32 v[22:23], v[22:23], v[126:127], v[26:27]
	v_pk_fma_f32 v[26:27], v[20:21], v[124:125], v[32:33]
	v_pk_fma_f32 v[20:21], v[18:19], v[122:123], v[30:31]
	v_pk_fma_f32 v[24:25], v[24:25], v[128:129], v[28:29]
	v_cvt_pk_bf16_f32 v18, v22, v23
	v_lshlrev_b32_e32 v22, 16, v72
	v_cvt_pk_bf16_f32 v19, v24, v25
	v_cvt_pk_bf16_f32 v20, v20, v21
	v_cvt_pk_bf16_f32 v21, v26, v27
	global_store_dwordx4 v[78:79], v[18:21], off offset:256
	v_and_b32_e32 v23, 0xffff0000, v72
	v_lshlrev_b32_e32 v24, 16, v73
	v_lshlrev_b32_e32 v18, 16, v70
	v_and_b32_e32 v19, 0xffff0000, v70
	v_lshlrev_b32_e32 v20, 16, v71
	v_and_b32_e32 v21, 0xffff0000, v71
	v_and_b32_e32 v25, 0xffff0000, v73
	v_pk_fma_f32 v[16:17], v[16:17], v[136:137], v[20:21]
	v_pk_fma_f32 v[14:15], v[14:15], v[134:135], v[18:19]
	v_pk_fma_f32 v[18:19], v[12:13], v[132:133], v[24:25]
	v_pk_fma_f32 v[12:13], v[10:11], v[130:131], v[22:23]
	v_cvt_pk_bf16_f32 v10, v14, v15
	v_cvt_pk_bf16_f32 v11, v16, v17
	v_lshlrev_b32_e32 v14, 16, v68
	v_cvt_pk_bf16_f32 v12, v12, v13
	v_cvt_pk_bf16_f32 v13, v18, v19
	global_store_dwordx4 v[76:77], v[10:13], off
	v_and_b32_e32 v15, 0xffff0000, v68
	v_lshlrev_b32_e32 v16, 16, v69
	v_lshlrev_b32_e32 v10, 16, v66
	v_and_b32_e32 v11, 0xffff0000, v66
	v_and_b32_e32 v17, 0xffff0000, v69
	v_lshlrev_b32_e32 v12, 16, v67
	v_and_b32_e32 v13, 0xffff0000, v67
	v_pk_fma_f32 v[6:7], v[6:7], v[126:127], v[10:11]
	v_pk_fma_f32 v[10:11], v[4:5], v[124:125], v[16:17]
	v_pk_fma_f32 v[4:5], v[2:3], v[122:123], v[14:15]
	v_pk_fma_f32 v[8:9], v[8:9], v[128:129], v[12:13]
	v_cvt_pk_bf16_f32 v2, v6, v7
	s_nop 0
	v_cvt_pk_bf16_f32 v3, v8, v9
	v_cvt_pk_bf16_f32 v4, v4, v5
	v_cvt_pk_bf16_f32 v5, v10, v11
	global_store_dwordx4 v[74:75], v[2:5], off offset:256
	s_branch .LBB0_1070

.LBB0_1269:
	s_ashr_i32 s13, s12, 31
	s_lshl_b64 s[12:13], s[12:13], 19
	s_lshl_b64 s[10:11], s[10:11], 2
	v_mov_b32_e32 v148, v1
	v_lshl_or_b32 v122, s76, 8, v192
	s_add_u32 s10, s35, s10
	s_addc_u32 s11, s61, s11
	v_add_u32_e32 v146, v122, v148
	v_ashrrev_i32_e32 v147, 31, v146
	v_lshl_add_u64 v[126:127], v[146:147], 2, s[10:11]
	s_add_u32 s10, s88, s12
	v_add_u32_e32 v148, v148, v190
	s_addc_u32 s11, s89, s13
	v_ashrrev_i32_e32 v149, 31, v148
	v_lshl_add_u64 v[146:147], v[146:147], 1, s[10:11]
	v_lshlrev_b64 v[148:149], 11, v[148:149]
	v_lshl_add_u64 v[176:177], v[146:147], 0, v[148:149]
	global_load_dwordx4 v[130:133], v[126:127], off offset:16
	global_load_dwordx4 v[134:137], v[126:127], off
	global_load_dwordx4 v[122:125], v[126:127], off offset:528
	s_nop 0
	global_load_dwordx4 v[126:129], v[126:127], off offset:512
	s_nop 0
	global_load_dwordx4 v[194:197], v[176:177], off
	global_load_dwordx4 v[198:201], v[176:177], off offset:256
	v_add_co_u32_e32 v188, vcc, s53, v176
	v_lshl_add_u64 v[184:185], v[176:177], 0, s[68:69]
	s_nop 0
	v_addc_co_u32_e32 v189, vcc, 0, v177, vcc
	global_load_dwordx4 v[202:205], v[188:189], off
	global_load_dwordx4 v[162:165], v[184:185], off offset:256
	s_mov_b32 s10, 0x10000
	v_add_co_u32_e32 v186, vcc, s10, v176
	v_lshl_add_u64 v[182:183], v[176:177], 0, s[70:71]
	s_nop 0
	v_addc_co_u32_e32 v187, vcc, 0, v177, vcc
	global_load_dwordx4 v[158:161], v[186:187], off
	global_load_dwordx4 v[154:157], v[182:183], off offset:256
	v_add_co_u32_e32 v180, vcc, s52, v176
	v_lshl_add_u64 v[178:179], v[176:177], 0, s[72:73]
	s_nop 0
	v_addc_co_u32_e32 v181, vcc, 0, v177, vcc
	global_load_dwordx4 v[150:153], v[180:181], off
	global_load_dwordx4 v[146:149], v[178:179], off offset:256
	v_add_co_u32_e32 v244, vcc, 0x40000, v176
	s_nop 1
	v_addc_co_u32_e32 v245, vcc, 0, v177, vcc
	global_load_dwordx4 v[236:239], v[244:245], off
	global_load_dwordx4 v[240:243], v[244:245], off offset:256
	v_add_co_u32_e32 v246, vcc, 0x48000, v176
	s_nop 1
	v_addc_co_u32_e32 v247, vcc, 0, v177, vcc
	global_load_dwordx4 v[236:239], v[246:247], off
	global_load_dwordx4 v[240:243], v[246:247], off offset:256
	v_add_co_u32_e32 v248, vcc, 0x50000, v176
	s_nop 1
	v_addc_co_u32_e32 v249, vcc, 0, v177, vcc
	global_load_dwordx4 v[236:239], v[248:249], off
	global_load_dwordx4 v[240:243], v[248:249], off offset:256
	v_add_co_u32_e32 v244, vcc, 0x58000, v176
	s_nop 1
	v_addc_co_u32_e32 v245, vcc, 0, v177, vcc
	global_load_dwordx4 v[236:239], v[244:245], off
	global_load_dwordx4 v[240:243], v[244:245], off offset:256
	s_mov_b32 s10, 0x40000
	s_mov_b32 s76, s65
	s_mov_b32 s12, s74
	s_mov_b64 s[16:17], s[8:9]
	s_mov_b64 s[14:15], s[6:7]
	s_waitcnt vmcnt(8)
	v_lshlrev_b32_e32 v206, 16, v194
	v_and_b32_e32 v207, 0xffff0000, v194
	v_lshlrev_b32_e32 v194, 16, v195
	v_and_b32_e32 v195, 0xffff0000, v195
	v_lshlrev_b32_e32 v208, 16, v196
	v_and_b32_e32 v209, 0xffff0000, v196
	v_lshlrev_b32_e32 v196, 16, v197
	v_and_b32_e32 v197, 0xffff0000, v197
	v_pk_fma_f32 v[144:145], v[144:145], v[136:137], v[194:195]
	v_pk_fma_f32 v[142:143], v[142:143], v[134:135], v[206:207]
	v_pk_fma_f32 v[194:195], v[140:141], v[132:133], v[196:197]
	v_pk_fma_f32 v[140:141], v[138:139], v[130:131], v[208:209]
	v_cvt_pk_bf16_f32 v138, v142, v143
	v_cvt_pk_bf16_f32 v139, v144, v145
	v_lshlrev_b32_e32 v142, 16, v200
	v_cvt_pk_bf16_f32 v140, v140, v141
	v_cvt_pk_bf16_f32 v141, v194, v195
	global_store_dwordx4 v[176:177], v[138:141], off
	v_and_b32_e32 v143, 0xffff0000, v200
	v_lshlrev_b32_e32 v144, 16, v201
	v_lshlrev_b32_e32 v138, 16, v198
	v_and_b32_e32 v139, 0xffff0000, v198
	v_and_b32_e32 v145, 0xffff0000, v201
	v_lshlrev_b32_e32 v140, 16, v199
	v_and_b32_e32 v141, 0xffff0000, v199
	v_pk_fma_f32 v[118:119], v[118:119], v[126:127], v[138:139]
	v_pk_fma_f32 v[138:139], v[116:117], v[124:125], v[144:145]
	v_pk_fma_f32 v[116:117], v[114:115], v[122:123], v[142:143]
	v_pk_fma_f32 v[120:121], v[120:121], v[128:129], v[140:141]
	v_cvt_pk_bf16_f32 v114, v118, v119
	v_lshlrev_b32_e32 v118, 16, v204
	v_cvt_pk_bf16_f32 v115, v120, v121
	v_cvt_pk_bf16_f32 v116, v116, v117
	v_cvt_pk_bf16_f32 v117, v138, v139
	global_store_dwordx4 v[176:177], v[114:117], off offset:256
	v_and_b32_e32 v119, 0xffff0000, v204
	v_lshlrev_b32_e32 v120, 16, v205
	v_lshlrev_b32_e32 v114, 16, v202
	v_and_b32_e32 v115, 0xffff0000, v202
	v_lshlrev_b32_e32 v116, 16, v203
	v_and_b32_e32 v117, 0xffff0000, v203
	v_and_b32_e32 v121, 0xffff0000, v205
	v_pk_fma_f32 v[112:113], v[112:113], v[136:137], v[116:117]
	v_pk_fma_f32 v[110:111], v[110:111], v[134:135], v[114:115]
	v_pk_fma_f32 v[114:115], v[108:109], v[132:133], v[120:121]
	v_pk_fma_f32 v[108:109], v[106:107], v[130:131], v[118:119]
	v_cvt_pk_bf16_f32 v106, v110, v111
	v_cvt_pk_bf16_f32 v107, v112, v113
	v_lshlrev_b32_e32 v110, 16, v164
	v_cvt_pk_bf16_f32 v108, v108, v109
	v_cvt_pk_bf16_f32 v109, v114, v115
	global_store_dwordx4 v[188:189], v[106:109], off
	v_and_b32_e32 v111, 0xffff0000, v164
	v_lshlrev_b32_e32 v112, 16, v165
	v_lshlrev_b32_e32 v106, 16, v162
	v_and_b32_e32 v107, 0xffff0000, v162
	v_and_b32_e32 v113, 0xffff0000, v165
	v_lshlrev_b32_e32 v108, 16, v163
	v_and_b32_e32 v109, 0xffff0000, v163
	v_pk_fma_f32 v[102:103], v[102:103], v[126:127], v[106:107]
	v_pk_fma_f32 v[106:107], v[100:101], v[124:125], v[112:113]
	v_pk_fma_f32 v[100:101], v[98:99], v[122:123], v[110:111]
	v_pk_fma_f32 v[104:105], v[104:105], v[128:129], v[108:109]
	v_cvt_pk_bf16_f32 v98, v102, v103
	v_lshlrev_b32_e32 v102, 16, v160
	v_cvt_pk_bf16_f32 v99, v104, v105
	v_cvt_pk_bf16_f32 v100, v100, v101
	v_cvt_pk_bf16_f32 v101, v106, v107
	global_store_dwordx4 v[184:185], v[98:101], off offset:256
	v_and_b32_e32 v103, 0xffff0000, v160
	v_lshlrev_b32_e32 v104, 16, v161
	v_lshlrev_b32_e32 v98, 16, v158
	v_and_b32_e32 v99, 0xffff0000, v158
	v_lshlrev_b32_e32 v100, 16, v159
	v_and_b32_e32 v101, 0xffff0000, v159
	v_and_b32_e32 v105, 0xffff0000, v161
	v_pk_fma_f32 v[96:97], v[96:97], v[136:137], v[100:101]
	v_pk_fma_f32 v[94:95], v[94:95], v[134:135], v[98:99]
	v_pk_fma_f32 v[98:99], v[92:93], v[132:133], v[104:105]
	v_pk_fma_f32 v[92:93], v[90:91], v[130:131], v[102:103]
	v_cvt_pk_bf16_f32 v90, v94, v95
	v_cvt_pk_bf16_f32 v91, v96, v97
	v_lshlrev_b32_e32 v94, 16, v156
	v_cvt_pk_bf16_f32 v92, v92, v93
	v_cvt_pk_bf16_f32 v93, v98, v99
	global_store_dwordx4 v[186:187], v[90:93], off
	v_and_b32_e32 v95, 0xffff0000, v156
	v_lshlrev_b32_e32 v96, 16, v157
	v_lshlrev_b32_e32 v90, 16, v154
	v_and_b32_e32 v91, 0xffff0000, v154
	v_and_b32_e32 v97, 0xffff0000, v157
	v_lshlrev_b32_e32 v92, 16, v155
	v_and_b32_e32 v93, 0xffff0000, v155
	v_pk_fma_f32 v[86:87], v[86:87], v[126:127], v[90:91]
	v_pk_fma_f32 v[90:91], v[84:85], v[124:125], v[96:97]
	v_pk_fma_f32 v[84:85], v[82:83], v[122:123], v[94:95]
	v_pk_fma_f32 v[88:89], v[88:89], v[128:129], v[92:93]
	v_cvt_pk_bf16_f32 v82, v86, v87
	v_lshlrev_b32_e32 v86, 16, v152
	v_cvt_pk_bf16_f32 v83, v88, v89
	v_cvt_pk_bf16_f32 v84, v84, v85
	v_cvt_pk_bf16_f32 v85, v90, v91
	global_store_dwordx4 v[182:183], v[82:85], off offset:256
	v_and_b32_e32 v87, 0xffff0000, v152
	v_lshlrev_b32_e32 v88, 16, v153
	v_lshlrev_b32_e32 v82, 16, v150
	v_and_b32_e32 v83, 0xffff0000, v150
	v_lshlrev_b32_e32 v84, 16, v151
	v_and_b32_e32 v85, 0xffff0000, v151
	v_and_b32_e32 v89, 0xffff0000, v153
	v_pk_fma_f32 v[80:81], v[80:81], v[136:137], v[84:85]
	v_pk_fma_f32 v[78:79], v[78:79], v[134:135], v[82:83]
	v_pk_fma_f32 v[82:83], v[76:77], v[132:133], v[88:89]
	v_pk_fma_f32 v[76:77], v[74:75], v[130:131], v[86:87]
	v_cvt_pk_bf16_f32 v74, v78, v79
	v_cvt_pk_bf16_f32 v75, v80, v81
	v_lshlrev_b32_e32 v78, 16, v148
	v_cvt_pk_bf16_f32 v76, v76, v77
	v_cvt_pk_bf16_f32 v77, v82, v83
	global_store_dwordx4 v[180:181], v[74:77], off
	v_and_b32_e32 v79, 0xffff0000, v148
	v_lshlrev_b32_e32 v80, 16, v149
	v_lshlrev_b32_e32 v74, 16, v146
	v_and_b32_e32 v75, 0xffff0000, v146
	v_and_b32_e32 v81, 0xffff0000, v149
	v_lshlrev_b32_e32 v76, 16, v147
	v_and_b32_e32 v77, 0xffff0000, v147
	v_pk_fma_f32 v[70:71], v[70:71], v[126:127], v[74:75]
	v_pk_fma_f32 v[74:75], v[68:69], v[124:125], v[80:81]
	v_pk_fma_f32 v[68:69], v[66:67], v[122:123], v[78:79]
	v_pk_fma_f32 v[72:73], v[72:73], v[128:129], v[76:77]
	v_cvt_pk_bf16_f32 v66, v70, v71
	v_add_co_u32_e32 v106, vcc, s10, v176
	v_cvt_pk_bf16_f32 v67, v72, v73
	v_cvt_pk_bf16_f32 v68, v68, v69
	v_cvt_pk_bf16_f32 v69, v74, v75
	global_store_dwordx4 v[178:179], v[66:69], off offset:256
	s_nop 0
	v_addc_co_u32_e32 v107, vcc, 0, v177, vcc
	v_lshl_add_u64 v[104:105], v[176:177], 0, s[2:3]
	global_load_dwordx4 v[80:83], v[106:107], off
	global_load_dwordx4 v[84:87], v[104:105], off offset:256
	v_add_co_u32_e32 v110, vcc, s54, v176
	s_mov_b64 s[10:11], 0x48000
	s_nop 0
	v_addc_co_u32_e32 v111, vcc, 0, v177, vcc
	v_lshl_add_u64 v[108:109], v[176:177], 0, s[10:11]
	global_load_dwordx4 v[88:91], v[110:111], off
	global_load_dwordx4 v[92:95], v[108:109], off offset:256
	s_mov_b64 s[10:11], 0x50000
	v_lshl_add_u64 v[78:79], v[176:177], 0, s[10:11]
	s_mov_b32 s10, 0x50000
	v_add_co_u32_e32 v112, vcc, s10, v176
	s_mov_b64 s[10:11], 0x58000
	s_nop 0
	v_addc_co_u32_e32 v113, vcc, 0, v177, vcc
	global_load_dwordx4 v[96:99], v[112:113], off
	global_load_dwordx4 v[100:103], v[78:79], off offset:256
	v_add_co_u32_e32 v76, vcc, s66, v176
	v_lshl_add_u64 v[74:75], v[176:177], 0, s[10:11]
	s_nop 0
	v_addc_co_u32_e32 v77, vcc, 0, v177, vcc
	global_load_dwordx4 v[70:73], v[76:77], off
	global_load_dwordx4 v[66:69], v[74:75], off offset:256
	s_and_b64 vcc, exec, s[0:1]
	s_waitcnt vmcnt(0)
	v_lshlrev_b32_e32 v114, 16, v80
	v_and_b32_e32 v115, 0xffff0000, v80
	v_lshlrev_b32_e32 v80, 16, v81
	v_and_b32_e32 v81, 0xffff0000, v81
	v_lshlrev_b32_e32 v116, 16, v82
	v_and_b32_e32 v117, 0xffff0000, v82
	v_lshlrev_b32_e32 v82, 16, v83
	v_and_b32_e32 v83, 0xffff0000, v83
	v_pk_fma_f32 v[64:65], v[64:65], v[136:137], v[80:81]
	v_pk_fma_f32 v[62:63], v[62:63], v[134:135], v[114:115]
	v_pk_fma_f32 v[80:81], v[60:61], v[132:133], v[82:83]
	v_pk_fma_f32 v[60:61], v[58:59], v[130:131], v[116:117]
	v_cvt_pk_bf16_f32 v58, v62, v63
	v_cvt_pk_bf16_f32 v59, v64, v65
	v_lshlrev_b32_e32 v62, 16, v86
	v_cvt_pk_bf16_f32 v60, v60, v61
	v_cvt_pk_bf16_f32 v61, v80, v81
	global_store_dwordx4 v[106:107], v[58:61], off
	v_and_b32_e32 v63, 0xffff0000, v86
	v_lshlrev_b32_e32 v64, 16, v87
	v_lshlrev_b32_e32 v58, 16, v84
	v_and_b32_e32 v59, 0xffff0000, v84
	v_and_b32_e32 v65, 0xffff0000, v87
	v_lshlrev_b32_e32 v60, 16, v85
	v_and_b32_e32 v61, 0xffff0000, v85
	v_pk_fma_f32 v[54:55], v[54:55], v[126:127], v[58:59]
	v_pk_fma_f32 v[58:59], v[52:53], v[124:125], v[64:65]
	v_pk_fma_f32 v[52:53], v[50:51], v[122:123], v[62:63]
	v_pk_fma_f32 v[56:57], v[56:57], v[128:129], v[60:61]
	v_cvt_pk_bf16_f32 v50, v54, v55
	v_lshlrev_b32_e32 v54, 16, v90
	v_cvt_pk_bf16_f32 v51, v56, v57
	v_cvt_pk_bf16_f32 v52, v52, v53
	v_cvt_pk_bf16_f32 v53, v58, v59
	global_store_dwordx4 v[104:105], v[50:53], off offset:256
	v_and_b32_e32 v55, 0xffff0000, v90
	v_lshlrev_b32_e32 v56, 16, v91
	v_lshlrev_b32_e32 v50, 16, v88
	v_and_b32_e32 v51, 0xffff0000, v88
	v_lshlrev_b32_e32 v52, 16, v89
	v_and_b32_e32 v53, 0xffff0000, v89
	v_and_b32_e32 v57, 0xffff0000, v91
	v_pk_fma_f32 v[48:49], v[48:49], v[136:137], v[52:53]
	v_pk_fma_f32 v[46:47], v[46:47], v[134:135], v[50:51]
	v_pk_fma_f32 v[50:51], v[44:45], v[132:133], v[56:57]
	v_pk_fma_f32 v[44:45], v[42:43], v[130:131], v[54:55]
	v_cvt_pk_bf16_f32 v42, v46, v47
	v_cvt_pk_bf16_f32 v43, v48, v49
	v_lshlrev_b32_e32 v46, 16, v94
	v_cvt_pk_bf16_f32 v44, v44, v45
	v_cvt_pk_bf16_f32 v45, v50, v51
	global_store_dwordx4 v[110:111], v[42:45], off
	v_and_b32_e32 v47, 0xffff0000, v94
	v_lshlrev_b32_e32 v48, 16, v95
	v_lshlrev_b32_e32 v42, 16, v92
	v_and_b32_e32 v43, 0xffff0000, v92
	v_and_b32_e32 v49, 0xffff0000, v95
	v_lshlrev_b32_e32 v44, 16, v93
	v_and_b32_e32 v45, 0xffff0000, v93
	v_pk_fma_f32 v[38:39], v[38:39], v[126:127], v[42:43]
	v_pk_fma_f32 v[42:43], v[36:37], v[124:125], v[48:49]
	v_pk_fma_f32 v[36:37], v[34:35], v[122:123], v[46:47]
	v_pk_fma_f32 v[40:41], v[40:41], v[128:129], v[44:45]
	v_cvt_pk_bf16_f32 v34, v38, v39
	v_lshlrev_b32_e32 v38, 16, v98
	v_cvt_pk_bf16_f32 v35, v40, v41
	v_cvt_pk_bf16_f32 v36, v36, v37
	v_cvt_pk_bf16_f32 v37, v42, v43
	global_store_dwordx4 v[108:109], v[34:37], off offset:256
	v_and_b32_e32 v39, 0xffff0000, v98
	v_lshlrev_b32_e32 v40, 16, v99
	v_lshlrev_b32_e32 v34, 16, v96
	v_and_b32_e32 v35, 0xffff0000, v96
	v_lshlrev_b32_e32 v36, 16, v97
	v_and_b32_e32 v37, 0xffff0000, v97
	v_and_b32_e32 v41, 0xffff0000, v99
	v_pk_fma_f32 v[32:33], v[32:33], v[136:137], v[36:37]
	v_pk_fma_f32 v[30:31], v[30:31], v[134:135], v[34:35]
	v_pk_fma_f32 v[34:35], v[28:29], v[132:133], v[40:41]
	v_pk_fma_f32 v[28:29], v[26:27], v[130:131], v[38:39]
	v_cvt_pk_bf16_f32 v26, v30, v31
	v_cvt_pk_bf16_f32 v27, v32, v33
	v_lshlrev_b32_e32 v30, 16, v102
	v_cvt_pk_bf16_f32 v28, v28, v29
	v_cvt_pk_bf16_f32 v29, v34, v35
	global_store_dwordx4 v[112:113], v[26:29], off
	v_and_b32_e32 v31, 0xffff0000, v102
	v_lshlrev_b32_e32 v32, 16, v103
	v_lshlrev_b32_e32 v26, 16, v100
	v_and_b32_e32 v27, 0xffff0000, v100
	v_and_b32_e32 v33, 0xffff0000, v103
	v_lshlrev_b32_e32 v28, 16, v101
	v_and_b32_e32 v29, 0xffff0000, v101
	v_pk_fma_f32 v[22:23], v[22:23], v[126:127], v[26:27]
	v_pk_fma_f32 v[26:27], v[20:21], v[124:125], v[32:33]
	v_pk_fma_f32 v[20:21], v[18:19], v[122:123], v[30:31]
	v_pk_fma_f32 v[24:25], v[24:25], v[128:129], v[28:29]
	v_cvt_pk_bf16_f32 v18, v22, v23
	v_lshlrev_b32_e32 v22, 16, v72
	v_cvt_pk_bf16_f32 v19, v24, v25
	v_cvt_pk_bf16_f32 v20, v20, v21
	v_cvt_pk_bf16_f32 v21, v26, v27
	global_store_dwordx4 v[78:79], v[18:21], off offset:256
	v_and_b32_e32 v23, 0xffff0000, v72
	v_lshlrev_b32_e32 v24, 16, v73
	v_lshlrev_b32_e32 v18, 16, v70
	v_and_b32_e32 v19, 0xffff0000, v70
	v_lshlrev_b32_e32 v20, 16, v71
	v_and_b32_e32 v21, 0xffff0000, v71
	v_and_b32_e32 v25, 0xffff0000, v73
	v_pk_fma_f32 v[16:17], v[16:17], v[136:137], v[20:21]
	v_pk_fma_f32 v[14:15], v[14:15], v[134:135], v[18:19]
	v_pk_fma_f32 v[18:19], v[12:13], v[132:133], v[24:25]
	v_pk_fma_f32 v[12:13], v[10:11], v[130:131], v[22:23]
	v_cvt_pk_bf16_f32 v10, v14, v15
	v_cvt_pk_bf16_f32 v11, v16, v17
	v_lshlrev_b32_e32 v14, 16, v68
	v_cvt_pk_bf16_f32 v12, v12, v13
	v_cvt_pk_bf16_f32 v13, v18, v19
	global_store_dwordx4 v[76:77], v[10:13], off
	v_and_b32_e32 v15, 0xffff0000, v68
	v_lshlrev_b32_e32 v16, 16, v69
	v_lshlrev_b32_e32 v10, 16, v66
	v_and_b32_e32 v11, 0xffff0000, v66
	v_and_b32_e32 v17, 0xffff0000, v69
	v_lshlrev_b32_e32 v12, 16, v67
	v_and_b32_e32 v13, 0xffff0000, v67
	v_pk_fma_f32 v[6:7], v[6:7], v[126:127], v[10:11]
	v_pk_fma_f32 v[10:11], v[4:5], v[124:125], v[16:17]
	v_pk_fma_f32 v[4:5], v[2:3], v[122:123], v[14:15]
	v_pk_fma_f32 v[8:9], v[8:9], v[128:129], v[12:13]
	v_cvt_pk_bf16_f32 v2, v6, v7
	s_nop 0
	v_cvt_pk_bf16_f32 v3, v8, v9
	v_cvt_pk_bf16_f32 v4, v4, v5
	v_cvt_pk_bf16_f32 v5, v10, v11
	global_store_dwordx4 v[74:75], v[2:5], off offset:256
	s_cbranch_vccnz .LBB0_1281
